# v22 + attention unit queue: next unit index prefetched one unit ahead except for the last 512 units of the phase (tail keeps just-in-time dequeue)
# baseline (speedup 1.0000x reference)
; #define LAS __attribute__((address_space(3)))
; #define INPTR(k) ({ int _i = (k); asm volatile("" : "+s"(_i)); (const float*)(GAS const float*)a.in[_i]; })
; __global__ void __launch_bounds__(512, 2) mega(Args a) {
;     ...
;         bf16_t* XN = (bf16_t*)(ws + WS_ACT);
;         bf16_t* PROJ = XN + (size_t)Tc * 1024;
;         bf16_t* QC = PROJ + (size_t)Tc * INP;
;         bf16_t* KVC = QC + (size_t)Tc * 768;
;         bf16_t* OC = KVC + (size_t)Tc * 1024;
;         bf16_t* MIX = OC + (size_t)Tc * 512;
;         bf16_t* OA = MIX + (size_t)Tc * 1024;
;         bf16_t* OB = OA + (size_t)Tc * 512;
;         float* PART = (float*)(OB + (size_t)Tc * 512);
;     ...
;                 unsigned* ctr = ctl + 64 * (1 + ck * 2 + l + 64 * rep);
;                 LAS int* s_unit = (LAS int*)(lds + LDS_CTRL);
;                 const float lam_init = (l == 0) ? 0.2f : 0.35550906f;
;                 float lam;
;                 { const float* lf = INPTR(3) + (size_t)l * 256; const float sa = wave_sum(lf[lane] * lf[64 + lane]), sb = wave_sum(lf[128 + lane] * lf[192 + lane]); lam = __expf(sa) - __expf(sb) + lam_init; lam = __uint_as_float(__builtin_amdgcn_readfirstlane(__float_as_uint(lam))); }
;                 const float* dgain = INPTR(4) + (size_t)l * 128;
;                 const int per_j = 16 * NB, nunits = 8 * per_j;
.LBB0_16:
	s_mul_i32 s6, s5, 0x67
	s_sext_i32_i16 s7, s6
	s_ashr_i32 s7, s7, 10
	s_bfe_u32 s6, s6, 0x1000f
	s_add_i32 s14, s7, s6
	s_bfe_i64 s[6:7], s[14:15], 0x100000
	s_add_i32 s5, s5, 9
	s_cmp_lt_u32 s5, 19
	v_writelane_b32 v253, s6, 50
	s_cselect_b64 s[22:23], -1, 0
	s_add_u32 s8, s74, 0x5000000
	v_writelane_b32 v253, s7, 51
	s_addc_u32 s9, s75, 0
	s_lshl_b64 s[6:7], s[16:17], 10
	s_lshl_b64 s[18:19], s[16:17], 11
	s_add_u32 s10, s8, s18
	s_addc_u32 s11, s9, s19
	s_mul_i32 s12, s16, 0x3600
	s_mul_hi_i32 s5, s16, 0x3600
	s_add_u32 s13, s10, s12
	s_addc_u32 s20, s11, s5
	s_mul_hi_i32 s5, s16, 0x600
	v_writelane_b32 v253, s16, 52
	s_mul_i32 s12, s16, 0x600
	s_add_u32 s12, s13, s12
	v_writelane_b32 v253, s17, 53
	v_writelane_b32 v253, s13, 54
	v_writelane_b32 v253, s20, 55
	s_addc_u32 s5, s20, s5
	v_writelane_b32 v253, s12, 56
	s_add_u32 s12, s12, s18
	v_writelane_b32 v253, s5, 57
	s_addc_u32 s5, s5, s19
	v_writelane_b32 v253, s12, 58
	s_add_u32 s12, s12, s6
	v_writelane_b32 v253, s5, 59
	s_addc_u32 s13, s5, s7
	s_add_u32 s5, s12, s18
	v_writelane_b32 v253, s18, 60
	s_addc_u32 s16, s13, s19
	v_writelane_b32 v251, s16, 0
	v_writelane_b32 v253, s19, 61
	v_writelane_b32 v253, s5, 62
	s_add_u32 s5, s5, s6
	v_writelane_b32 v253, s5, 63
	s_addc_u32 s5, s16, s7
	v_writelane_b32 v251, s5, 1
	s_mov_b64 s[18:19], -1
	s_cmp_lt_i32 s15, 4
	s_mov_b64 s[16:17], 0
	v_writelane_b32 v251, s92, 2
	v_writelane_b32 v251, s15, 3
	s_cbranch_scc1 .LBB0_1233
	s_cmp_eq_u32 s15, 4
	s_mov_b64 s[16:17], -1
	s_cbranch_scc0 .LBB0_1232
	s_sext_i32_i16 s5, s14
	s_lshl_b32 s4, s4, 1
	s_add_i32 s5, s5, s4
	s_lshl_b32 s4, s5, 6
	s_add_i32 s4, s4, 64
	s_ashr_i32 s5, s4, 31
	s_lshl_b64 s[4:5], s[4:5], 2
	v_writelane_b32 v251, s28, 4
	s_add_u32 s4, s74, s4
	s_addc_u32 s5, s75, s5
	v_writelane_b32 v251, s29, 5
	v_writelane_b32 v251, s4, 6
	v_readlane_b32 s16, v253, 50
	v_readlane_b32 s17, v253, 51
	v_writelane_b32 v251, s5, 7
	s_mov_b32 s4, 3
	s_ashr_i32 s5, s4, 31
	s_lshl_b64 s[4:5], s[4:5], 3
	s_add_u32 s4, s0, s4
	s_addc_u32 s5, s1, s5
	s_load_dwordx2 s[4:5], s[4:5], 0x0
	s_lshl_b64 s[6:7], s[16:17], 10
	v_lshlrev_b32_e32 v0, 2, v203
	v_cmp_lt_i32_e32 vcc, v185, v184
	v_writelane_b32 v251, s22, 8
	s_waitcnt lgkmcnt(0)
	s_add_u32 s4, s4, s6
	s_addc_u32 s5, s5, s7
	global_load_dword v1, v0, s[4:5]
	global_load_dword v2, v0, s[4:5] offset:256
	global_load_dword v3, v0, s[4:5] offset:512
	s_nop 0
	global_load_dword v0, v0, s[4:5] offset:768
	v_cndmask_b32_e32 v6, v183, v185, vcc
	v_lshlrev_b32_e32 v6, 2, v6
	v_cmp_lt_i32_e32 vcc, v186, v184
	s_mov_b32 s4, 4
	s_ashr_i32 s5, s4, 31
	v_cndmask_b32_e32 v7, v183, v186, vcc
	v_lshlrev_b32_e32 v7, 2, v7
	v_cmp_lt_i32_e32 vcc, v187, v184
	s_lshl_b64 s[4:5], s[4:5], 3
	s_add_u32 s4, s0, s4
	v_cndmask_b32_e32 v8, v183, v187, vcc
	v_cmp_lt_i32_e32 vcc, v188, v184
	s_addc_u32 s5, s1, s5
	s_load_dwordx2 s[4:5], s[4:5], 0x0
	v_cndmask_b32_e32 v9, v183, v188, vcc
	v_cmp_lt_i32_e32 vcc, v189, v184
	s_lshl_b64 s[6:7], s[16:17], 9
	v_cndmask_b32_e64 v4, v193, v194, s[22:23]
	s_mul_i32 s14, s92, 0x2200
	s_waitcnt lgkmcnt(0)
	s_add_u32 s42, s4, s6
	s_addc_u32 s43, s5, s7
	s_add_i32 s4, s14, 0
	v_writelane_b32 v251, s23, 9
	s_add_i32 s71, s4, 0x12800
	v_cmp_eq_u32_e64 s[62:63], 0, v202
	s_lshl_b32 s73, s92, 5
	v_sub_f32_e32 v152, 1.0, v4
	s_waitcnt vmcnt(0)
	v_mul_f32_e32 v10, v1, v2
	ds_bpermute_b32 v10, v6, v10
	s_waitcnt vmcnt(0)
	v_mul_f32_e32 v11, v3, v0
	ds_bpermute_b32 v6, v6, v11
	v_cndmask_b32_e32 v11, v183, v189, vcc
	v_cmp_lt_i32_e32 vcc, v190, v184
	s_waitcnt lgkmcnt(1)
	v_fmac_f32_e32 v10, v1, v2
	s_waitcnt lgkmcnt(0)
	v_fmac_f32_e32 v6, v3, v0
	ds_bpermute_b32 v0, v7, v10
	ds_bpermute_b32 v1, v7, v6
	v_lshlrev_b32_e32 v3, 2, v8
	v_cndmask_b32_e32 v2, v183, v190, vcc
	v_lshlrev_b32_e32 v7, 2, v9
	s_waitcnt lgkmcnt(1)
	v_add_f32_e32 v0, v10, v0
	s_waitcnt lgkmcnt(0)
	v_add_f32_e32 v1, v6, v1
	ds_bpermute_b32 v6, v3, v0
	ds_bpermute_b32 v3, v3, v1
	v_lshlrev_b32_e32 v174, 2, v2
	v_lshlrev_b32_e32 v8, 2, v11
	s_waitcnt lgkmcnt(1)
	v_add_f32_e32 v0, v0, v6
	s_waitcnt lgkmcnt(0)
	v_add_f32_e32 v1, v1, v3
	ds_bpermute_b32 v2, v7, v0
	ds_bpermute_b32 v3, v7, v1
	s_waitcnt lgkmcnt(1)
	v_add_f32_e32 v0, v0, v2
	s_waitcnt lgkmcnt(0)
	v_add_f32_e32 v1, v1, v3
	ds_bpermute_b32 v2, v8, v0
	ds_bpermute_b32 v3, v8, v1
	s_waitcnt lgkmcnt(1)
	v_add_f32_e32 v0, v0, v2
	s_waitcnt lgkmcnt(0)
	v_add_f32_e32 v1, v1, v3
	ds_bpermute_b32 v2, v174, v0
	ds_bpermute_b32 v3, v174, v1
	s_waitcnt lgkmcnt(1)
	v_add_f32_e32 v0, v0, v2
	s_waitcnt lgkmcnt(0)
	v_add_f32_e32 v1, v1, v3
	v_mul_f32_e32 v0, 0x3fb8aa3b, v0
	v_mul_f32_e32 v1, 0x3fb8aa3b, v1
	v_exp_f32_e32 v0, v0
	v_exp_f32_e32 v1, v1
	s_nop 0
	v_sub_f32_e32 v0, v0, v1
	v_add_f32_e32 v0, v4, v0
	s_nop 0
	v_readfirstlane_b32 s4, v0
	s_nop 1
	v_writelane_b32 v251, s4, 10
	v_writelane_b32 v251, s62, 11
	s_nop 1
	v_writelane_b32 v251, s63, 12
	v_writelane_b32 v251, s73, 13
	v_mov_b32_e32 v255, 0
	s_branch .LBB0_140

; __global__ void __launch_bounds__(512, 2) mega(Args a) {
;     ...
;                 for (;;) {
;                     if (tid == 0) *s_unit = (int)atomicAdd(ctr, 1u);
;                     __syncthreads();
;                     const int u = *s_unit;
;                     __syncthreads();
;                     if (u >= nunits) break;
.LBB0_140:
	s_mov_b32 m0, 0
	s_and_saveexec_b64 s[14:15], s[62:63]
	s_cbranch_execz .LBB0_142
	v_cmp_ne_u32_e32 vcc, 0, v255
	s_cbranch_vccz .Lmy_dq_sync
	v_mov_b32_e32 v0, v254
	s_branch .Lmy_dq_have
.Lmy_dq_sync:
	v_readlane_b32 s4, v251, 6
	v_readlane_b32 s5, v251, 7
	s_nop 1
	v_mov_b64_e32 v[0:1], s[4:5]
	global_atomic_add v0, v[0:1], v191, off sc0
	s_waitcnt vmcnt(0)
.Lmy_dq_have:
	v_readlane_b32 s4, v253, 26
	s_nop 1
	v_mov_b32_e32 v1, s4
	ds_write_b32 v1, v0
	s_add_i32 s4, s70, 0xfffffe00
	v_cmp_gt_i32_e32 vcc, s4, v0
	s_nop 1
	v_cndmask_b32_e64 v255, 0, 1, vcc
	s_cbranch_vccz .LBB0_142
	v_readlane_b32 s4, v251, 6
	v_readlane_b32 s5, v251, 7
	s_nop 1
	v_mov_b64_e32 v[0:1], s[4:5]
	global_atomic_add v254, v[0:1], v191, off sc0
